# ssm pass 3 scan: u rows loaded per lane into the MFMA operand registers one 16-step block ahead, q loop unrolled
# baseline (speedup 1.0000x reference)
; #define LAS __attribute__((address_space(3)))
; __device__ __forceinline__ void ssm_pass3h(CArgs* ap, const float* COEF, int l, const bf16_t* PROJ, const float* SST, bf16_t* YS, LAS unsigned char* wlds, int unit, int lane) {
;     ...
;     const size_t row0 = (size_t)(b * SEQ + c * 128);
;     const bf16_t* up = PROJ + row0 * INW + 2560 + g * 16;
;     LAS float* Hf = (LAS float*)wlds;
;     u32x4 wn[8];
; #pragma unroll
;     for (int tt = 0; tt < 4; ++tt) { wn[2 * tt] = ((const u32x4*)(up + (size_t)tt * INW))[0]; wn[2 * tt + 1] = ((const u32x4*)(up + (size_t)tt * INW))[1]; }
.LBB0_148:
	s_lshl_b32 s0, s9, 2
	s_and_b32 s0, s0, 0xffffe000
	s_lshl_b32 s1, s3, 7
	s_or_b32 s0, s0, s1
	s_ashr_i32 s1, s0, 31
	s_mul_i32 s10, s0, 0x4800
	s_mul_hi_i32 s3, s0, 0x4800
	s_add_u32 s10, s68, s10
	s_addc_u32 s3, s69, s3
	s_lshl_b32 s78, s2, 1
	s_add_u32 s10, s10, s78
	s_addc_u32 s11, s3, 0
	s_add_u32 s2, s10, 0x1400
	s_addc_u32 s3, s11, 0
	s_add_u32 s12, s10, 0x5c00
	v_mov_b32_e32 v0, 0x5000
	v_and_b32_e32 v224, 3, v166
	v_mul_u32_u24_e32 v224, 0x4800, v224
	v_mov_b32_e32 v208, v101
	v_mov_b32_e32 v209, v103
	v_mov_b32_e32 v210, v102
	v_mov_b32_e32 v211, v104
	v_mov_b32_e32 v212, v105
	v_mov_b32_e32 v213, v107
	v_mov_b32_e32 v214, v106
	v_mov_b32_e32 v215, v108
	v_mov_b32_e32 v216, v109
	v_mov_b32_e32 v217, v111
	v_mov_b32_e32 v218, v110
	v_mov_b32_e32 v219, v112
	v_mov_b32_e32 v220, v113
	v_mov_b32_e32 v221, v115
	v_mov_b32_e32 v222, v114
	v_mov_b32_e32 v223, v116
	global_load_dwordx4 v[20:23], v224, s[2:3] offset:16
	global_load_dwordx4 v[24:27], v224, s[2:3]
	s_add_u32 s12, s2, 0x12000
	s_addc_u32 s13, s3, 0
	global_load_dwordx4 v[28:31], v224, s[12:13] offset:16
	global_load_dwordx4 v[32:35], v224, s[12:13]
	s_add_u32 s12, s2, 0x24000
	s_addc_u32 s13, s3, 0
	global_load_dwordx4 v[36:39], v224, s[12:13] offset:16
	global_load_dwordx4 v[40:43], v224, s[12:13]
	s_add_u32 s12, s2, 0x36000
	s_addc_u32 s13, s3, 0
	global_load_dwordx4 v[44:47], v224, s[12:13] offset:16
	global_load_dwordx4 v[48:51], v224, s[12:13]
	v_lshl_add_u64 v[92:93], v[80:81], 0, s[78:79]
	v_pk_mov_b32 v[94:95], v[2:3], v[2:3] op_sel:[1,0]
	s_mov_b32 s10, 0
	s_waitcnt vmcnt(12)
	v_xor_b32_e32 v89, 0x80000000, v64
	v_xor_b32_e32 v117, 0x80000000, v65
	v_xor_b32_e32 v118, 0x80000000, v66
	v_xor_b32_e32 v119, 0x80000000, v67
	s_waitcnt vmcnt(11)
	v_xor_b32_e32 v120, 0x80000000, v60
	v_xor_b32_e32 v121, 0x80000000, v61
	v_xor_b32_e32 v122, 0x80000000, v62
	v_xor_b32_e32 v123, 0x80000000, v63
	s_waitcnt vmcnt(10)
	v_xor_b32_e32 v124, 0x80000000, v56
	v_xor_b32_e32 v125, 0x80000000, v57
	v_xor_b32_e32 v126, 0x80000000, v58
	v_xor_b32_e32 v127, 0x80000000, v59
	s_waitcnt vmcnt(9)
	v_xor_b32_e32 v128, 0x80000000, v52
	v_xor_b32_e32 v129, 0x80000000, v53
	v_xor_b32_e32 v130, 0x80000000, v54
	v_xor_b32_e32 v131, 0x80000000, v55
	s_mov_b32 s11, 0

; __device__ __forceinline__ void ssm_pass3h(CArgs* ap, const float* COEF, int l, const bf16_t* PROJ, const float* SST, bf16_t* YS, LAS unsigned char* wlds, int unit, int lane) {
;     ...
;         for (int q = 0; q < 4; ++q) {
;             const int t = 16 * blk + 4 * q;
;             u32x4 wc[8];
; #pragma unroll
;             for (int j = 0; j < 8; ++j) wc[j] = wn[j];
;             const int tn = (t + 4 < 128) ? t + 4 : t;
; #pragma unroll
;             for (int tt = 0; tt < 4; ++tt) { wn[2 * tt] = ((const u32x4*)(up + (size_t)(tn + tt) * INW))[0]; wn[2 * tt + 1] = ((const u32x4*)(up + (size_t)(tn + tt) * INW))[1]; }
; #pragma unroll
;             for (int tt = 0; tt < 4; ++tt) {
;                 const u32x4 w0 = wc[2 * tt], w1 = wc[2 * tt + 1];
;                 const unsigned u2[8] = {w0.x, w0.y, w0.z, w0.w, w1.x, w1.y, w1.z, w1.w};
;                 float br_ = 0.f, bi_ = 0.f;
; #pragma unroll
;                 for (int k = 0; k < 8; ++k) { br_ = __builtin_amdgcn_fdot2_f32_bf16(__builtin_bit_cast(bf16x2v, bbr2[k]), __builtin_bit_cast(bf16x2v, u2[k]), br_, false);
;                                                bi_ = __builtin_amdgcn_fdot2_f32_bf16(__builtin_bit_cast(bf16x2v, bbi2[k]), __builtin_bit_cast(bf16x2v, u2[k]), bi_, false); }
;                 const float nr = abr * hr - abi * hi + br_, ni = abr * hi + abi * hr + bi_; hr = nr; hi = ni;
;                 Hf[(4 * q + tt) * 132 + lane] = hr; Hf[(4 * q + tt) * 132 + 64 + lane] = hi;
;             }
.LBB0_150:
	s_add_i32 s13, s14, 4
	s_add_i32 s78, s14, 16
	s_cmpk_lt_u32 s14, 0x70
	s_cselect_b32 s78, s78, s14
	s_mul_i32 s78, s78, 0x2400
	s_lshl_b64 s[14:15], s[78:79], 1
	s_add_u32 s14, s2, s14
	s_addc_u32 s15, s3, s15
	s_waitcnt vmcnt(10)
	v_mfma_f32_4x4x4_16b_bf16 v[144:147], v[24:25], v[208:209], 0
	v_mfma_f32_4x4x4_16b_bf16 v[148:151], v[24:25], v[210:211], 0
	s_nop 0
	v_mfma_f32_4x4x4_16b_bf16 v[144:147], v[26:27], v[212:213], v[144:147]
	v_mfma_f32_4x4x4_16b_bf16 v[148:151], v[26:27], v[214:215], v[148:151]
	s_nop 0
	v_mfma_f32_4x4x4_16b_bf16 v[144:147], v[20:21], v[216:217], v[144:147]
	v_mfma_f32_4x4x4_16b_bf16 v[148:151], v[20:21], v[218:219], v[148:151]
	s_nop 0
	v_mfma_f32_4x4x4_16b_bf16 v[144:147], v[22:23], v[220:221], v[144:147]
	v_mfma_f32_4x4x4_16b_bf16 v[148:151], v[22:23], v[222:223], v[148:151]
	global_load_dwordx4 v[20:23], v224, s[14:15] offset:16
	global_load_dwordx4 v[24:27], v224, s[14:15]
	v_add_u32_e32 v97, s12, v99
	v_add_u32_e32 v184, 32, v97
	v_add_u32_e32 v185, 48, v97
	v_pk_mul_f32 v[152:153], v[2:3], v[90:91]
	v_pk_mul_f32 v[154:155], v[94:95], v[90:91]
	v_sub_f32_e32 v152, v152, v153
	v_add_f32_e32 v153, v154, v155
	v_add_f32_e32 v90, v144, v152
	v_add_f32_e32 v91, v148, v153
	ds_write2st64_b32 v97, v90, v91 offset1:1
	v_pk_mul_f32 v[152:153], v[2:3], v[90:91]
	v_pk_mul_f32 v[154:155], v[94:95], v[90:91]
	v_sub_f32_e32 v152, v152, v153
	v_add_f32_e32 v153, v154, v155
	v_add_f32_e32 v90, v145, v152
	v_add_f32_e32 v91, v149, v153
	ds_write2_b32 v97, v90, v91 offset0:132 offset1:196
	v_pk_mul_f32 v[152:153], v[2:3], v[90:91]
	v_pk_mul_f32 v[154:155], v[94:95], v[90:91]
	v_sub_f32_e32 v152, v152, v153
	v_add_f32_e32 v153, v154, v155
	v_add_f32_e32 v90, v146, v152
	v_add_f32_e32 v91, v150, v153
	ds_write2st64_b32 v184, v90, v91 offset0:4 offset1:5
	v_pk_mul_f32 v[152:153], v[2:3], v[90:91]
	v_pk_mul_f32 v[154:155], v[94:95], v[90:91]
	v_sub_f32_e32 v152, v152, v153
	v_add_f32_e32 v153, v154, v155
	v_add_f32_e32 v90, v147, v152
	v_add_f32_e32 v91, v151, v153
	ds_write2st64_b32 v185, v90, v91 offset0:6 offset1:7
	s_addk_i32 s12, 0x840
	s_mov_b32 s14, s13
	s_add_i32 s13, s14, 4
	s_add_i32 s78, s14, 16
	s_cmpk_lt_u32 s14, 0x70
	s_cselect_b32 s78, s78, s14
	s_mul_i32 s78, s78, 0x2400
	s_lshl_b64 s[14:15], s[78:79], 1
	s_add_u32 s14, s2, s14
	s_addc_u32 s15, s3, s15
	s_waitcnt vmcnt(10)
	v_mfma_f32_4x4x4_16b_bf16 v[144:147], v[32:33], v[208:209], 0
	v_mfma_f32_4x4x4_16b_bf16 v[148:151], v[32:33], v[210:211], 0
	s_nop 0
	v_mfma_f32_4x4x4_16b_bf16 v[144:147], v[34:35], v[212:213], v[144:147]
	v_mfma_f32_4x4x4_16b_bf16 v[148:151], v[34:35], v[214:215], v[148:151]
	s_nop 0
	v_mfma_f32_4x4x4_16b_bf16 v[144:147], v[28:29], v[216:217], v[144:147]
	v_mfma_f32_4x4x4_16b_bf16 v[148:151], v[28:29], v[218:219], v[148:151]
	s_nop 0
	v_mfma_f32_4x4x4_16b_bf16 v[144:147], v[30:31], v[220:221], v[144:147]
	v_mfma_f32_4x4x4_16b_bf16 v[148:151], v[30:31], v[222:223], v[148:151]
	global_load_dwordx4 v[28:31], v224, s[14:15] offset:16
	global_load_dwordx4 v[32:35], v224, s[14:15]
	v_add_u32_e32 v97, s12, v99
	v_add_u32_e32 v184, 32, v97
	v_add_u32_e32 v185, 48, v97
	v_pk_mul_f32 v[152:153], v[2:3], v[90:91]
	v_pk_mul_f32 v[154:155], v[94:95], v[90:91]
	v_sub_f32_e32 v152, v152, v153
	v_add_f32_e32 v153, v154, v155
	v_add_f32_e32 v90, v144, v152
	v_add_f32_e32 v91, v148, v153
	ds_write2st64_b32 v97, v90, v91 offset1:1
	v_pk_mul_f32 v[152:153], v[2:3], v[90:91]
	v_pk_mul_f32 v[154:155], v[94:95], v[90:91]
	v_sub_f32_e32 v152, v152, v153
	v_add_f32_e32 v153, v154, v155
	v_add_f32_e32 v90, v145, v152
	v_add_f32_e32 v91, v149, v153
	ds_write2_b32 v97, v90, v91 offset0:132 offset1:196
	v_pk_mul_f32 v[152:153], v[2:3], v[90:91]
	v_pk_mul_f32 v[154:155], v[94:95], v[90:91]
	v_sub_f32_e32 v152, v152, v153
	v_add_f32_e32 v153, v154, v155
	v_add_f32_e32 v90, v146, v152
	v_add_f32_e32 v91, v150, v153
	ds_write2st64_b32 v184, v90, v91 offset0:4 offset1:5
	v_pk_mul_f32 v[152:153], v[2:3], v[90:91]
	v_pk_mul_f32 v[154:155], v[94:95], v[90:91]
	v_sub_f32_e32 v152, v152, v153
	v_add_f32_e32 v153, v154, v155
	v_add_f32_e32 v90, v147, v152
	v_add_f32_e32 v91, v151, v153
	ds_write2st64_b32 v185, v90, v91 offset0:6 offset1:7
	s_addk_i32 s12, 0x840
	s_mov_b32 s14, s13
	s_add_i32 s13, s14, 4
	s_add_i32 s78, s14, 16
	s_cmpk_lt_u32 s14, 0x70
	s_cselect_b32 s78, s78, s14
	s_mul_i32 s78, s78, 0x2400
	s_lshl_b64 s[14:15], s[78:79], 1
	s_add_u32 s14, s2, s14
	s_addc_u32 s15, s3, s15
	s_waitcnt vmcnt(10)
	v_mfma_f32_4x4x4_16b_bf16 v[144:147], v[40:41], v[208:209], 0
	v_mfma_f32_4x4x4_16b_bf16 v[148:151], v[40:41], v[210:211], 0
	s_nop 0
	v_mfma_f32_4x4x4_16b_bf16 v[144:147], v[42:43], v[212:213], v[144:147]
	v_mfma_f32_4x4x4_16b_bf16 v[148:151], v[42:43], v[214:215], v[148:151]
	s_nop 0
	v_mfma_f32_4x4x4_16b_bf16 v[144:147], v[36:37], v[216:217], v[144:147]
	v_mfma_f32_4x4x4_16b_bf16 v[148:151], v[36:37], v[218:219], v[148:151]
	s_nop 0
	v_mfma_f32_4x4x4_16b_bf16 v[144:147], v[38:39], v[220:221], v[144:147]
	v_mfma_f32_4x4x4_16b_bf16 v[148:151], v[38:39], v[222:223], v[148:151]
	global_load_dwordx4 v[36:39], v224, s[14:15] offset:16
	global_load_dwordx4 v[40:43], v224, s[14:15]
	v_add_u32_e32 v97, s12, v99
	v_add_u32_e32 v184, 32, v97
	v_add_u32_e32 v185, 48, v97
	v_pk_mul_f32 v[152:153], v[2:3], v[90:91]
	v_pk_mul_f32 v[154:155], v[94:95], v[90:91]
	v_sub_f32_e32 v152, v152, v153
	v_add_f32_e32 v153, v154, v155
	v_add_f32_e32 v90, v144, v152
	v_add_f32_e32 v91, v148, v153
	ds_write2st64_b32 v97, v90, v91 offset1:1
	v_pk_mul_f32 v[152:153], v[2:3], v[90:91]
	v_pk_mul_f32 v[154:155], v[94:95], v[90:91]
	v_sub_f32_e32 v152, v152, v153
	v_add_f32_e32 v153, v154, v155
	v_add_f32_e32 v90, v145, v152
	v_add_f32_e32 v91, v149, v153
	ds_write2_b32 v97, v90, v91 offset0:132 offset1:196
	v_pk_mul_f32 v[152:153], v[2:3], v[90:91]
	v_pk_mul_f32 v[154:155], v[94:95], v[90:91]
	v_sub_f32_e32 v152, v152, v153
	v_add_f32_e32 v153, v154, v155
	v_add_f32_e32 v90, v146, v152
	v_add_f32_e32 v91, v150, v153
	ds_write2st64_b32 v184, v90, v91 offset0:4 offset1:5
	v_pk_mul_f32 v[152:153], v[2:3], v[90:91]
	v_pk_mul_f32 v[154:155], v[94:95], v[90:91]
	v_sub_f32_e32 v152, v152, v153
	v_add_f32_e32 v153, v154, v155
	v_add_f32_e32 v90, v147, v152
	v_add_f32_e32 v91, v151, v153
	ds_write2st64_b32 v185, v90, v91 offset0:6 offset1:7
	s_addk_i32 s12, 0x840
	s_mov_b32 s14, s13
	s_add_i32 s13, s14, 4
	s_add_i32 s78, s14, 16
	s_cmpk_lt_u32 s14, 0x70
	s_cselect_b32 s78, s78, s14
	s_mul_i32 s78, s78, 0x2400
	s_lshl_b64 s[14:15], s[78:79], 1
	s_add_u32 s14, s2, s14
	s_addc_u32 s15, s3, s15
	s_waitcnt vmcnt(10)
; __device__ __forceinline__ float gelu_t(float x) { const float p = __builtin_fmaf(x * x, -0.10294324f, -2.30220819f); return x * __builtin_amdgcn_rcpf(1.f + __builtin_amdgcn_exp2f(x * p)); }
; #define LAS __attribute__((address_space(3)))
; __device__ __forceinline__ unsigned f2bf(float f) { unsigned u = __builtin_bit_cast(unsigned, f); return (u + 0x7fffu + ((u >> 16) & 1u)) >> 16; }
; __device__ __forceinline__ void ssm_pass3h(CArgs* ap, const float* COEF, int l, const bf16_t* PROJ, const float* SST, bf16_t* YS, LAS unsigned char* wlds, int unit, int lane) {
;     ...
;             for (int tt = 0; tt < 4; ++tt) {
;                 const u32x4 w0 = wc[2 * tt], w1 = wc[2 * tt + 1];
;                 const unsigned u2[8] = {w0.x, w0.y, w0.z, w0.w, w1.x, w1.y, w1.z, w1.w};
;                 float br_ = 0.f, bi_ = 0.f;
; #pragma unroll
;                 for (int k = 0; k < 8; ++k) { br_ = __builtin_amdgcn_fdot2_f32_bf16(__builtin_bit_cast(bf16x2v, bbr2[k]), __builtin_bit_cast(bf16x2v, u2[k]), br_, false);
;                                                bi_ = __builtin_amdgcn_fdot2_f32_bf16(__builtin_bit_cast(bf16x2v, bbi2[k]), __builtin_bit_cast(bf16x2v, u2[k]), bi_, false); }
;                 const float nr = abr * hr - abi * hi + br_, ni = abr * hi + abi * hr + bi_; hr = nr; hi = ni;
;                 Hf[(4 * q + tt) * 132 + lane] = hr; Hf[(4 * q + tt) * 132 + 64 + lane] = hi;
;             }
;         }
;         asm volatile("s_waitcnt lgkmcnt(0)" ::: "memory");
;         f32x4 y = (f32x4){0.f, 0.f, 0.f, 0.f};
; #pragma unroll
;         for (int j = 0; j < 8; ++j) {
;             const f32x4 a4 = *(const LAS f32x4*)(Hf + fr * 132 + 16 * j + 4 * fq);
; #pragma unroll
;             for (int r = 0; r < 4; ++r) y = __builtin_amdgcn_mfma_f32_16x16x4f32(a4[r], cmB[4 * j + r], y, 0, 0, 0);
;         }
;         asm volatile("s_waitcnt lgkmcnt(0)" ::: "memory");
; #pragma unroll
;         for (int i = 0; i < 4; ++i) {
;             const size_t row = row0 + 16 * blk + 4 * fq + i;
;             YS[row * 512 + g * 16 + fr] = (bf16_t)f2bf(gelu_t(y[i] + dsk * __uint_as_float(((unsigned)uq[i]) << 16)));
;         }
	v_mfma_f32_4x4x4_16b_bf16 v[144:147], v[48:49], v[208:209], 0
	v_mfma_f32_4x4x4_16b_bf16 v[148:151], v[48:49], v[210:211], 0
	s_nop 0
	v_mfma_f32_4x4x4_16b_bf16 v[144:147], v[50:51], v[212:213], v[144:147]
	v_mfma_f32_4x4x4_16b_bf16 v[148:151], v[50:51], v[214:215], v[148:151]
	s_nop 0
	v_mfma_f32_4x4x4_16b_bf16 v[144:147], v[44:45], v[216:217], v[144:147]
	v_mfma_f32_4x4x4_16b_bf16 v[148:151], v[44:45], v[218:219], v[148:151]
	s_nop 0
	v_mfma_f32_4x4x4_16b_bf16 v[144:147], v[46:47], v[220:221], v[144:147]
	v_mfma_f32_4x4x4_16b_bf16 v[148:151], v[46:47], v[222:223], v[148:151]
	global_load_dwordx4 v[44:47], v224, s[14:15] offset:16
	global_load_dwordx4 v[48:51], v224, s[14:15]
	v_add_u32_e32 v97, s12, v99
	v_add_u32_e32 v184, 32, v97
	v_add_u32_e32 v185, 48, v97
	v_pk_mul_f32 v[152:153], v[2:3], v[90:91]
	v_pk_mul_f32 v[154:155], v[94:95], v[90:91]
	v_sub_f32_e32 v152, v152, v153
	v_add_f32_e32 v153, v154, v155
	v_add_f32_e32 v90, v144, v152
	v_add_f32_e32 v91, v148, v153
	ds_write2st64_b32 v97, v90, v91 offset1:1
	v_pk_mul_f32 v[152:153], v[2:3], v[90:91]
	v_pk_mul_f32 v[154:155], v[94:95], v[90:91]
	v_sub_f32_e32 v152, v152, v153
	v_add_f32_e32 v153, v154, v155
	v_add_f32_e32 v90, v145, v152
	v_add_f32_e32 v91, v149, v153
	ds_write2_b32 v97, v90, v91 offset0:132 offset1:196
	v_pk_mul_f32 v[152:153], v[2:3], v[90:91]
	v_pk_mul_f32 v[154:155], v[94:95], v[90:91]
	v_sub_f32_e32 v152, v152, v153
	v_add_f32_e32 v153, v154, v155
	v_add_f32_e32 v90, v146, v152
	v_add_f32_e32 v91, v150, v153
	ds_write2st64_b32 v184, v90, v91 offset0:4 offset1:5
	v_pk_mul_f32 v[152:153], v[2:3], v[90:91]
	v_pk_mul_f32 v[154:155], v[94:95], v[90:91]
	v_sub_f32_e32 v152, v152, v153
	v_add_f32_e32 v153, v154, v155
	v_add_f32_e32 v90, v147, v152
	v_add_f32_e32 v91, v151, v153
	ds_write2st64_b32 v185, v90, v91 offset0:6 offset1:7
	s_addk_i32 s12, 0x840
	s_mov_b32 s14, s13
	s_waitcnt lgkmcnt(0)
	ds_read_b128 v[144:147], v100
	ds_read_b128 v[148:151], v100 offset:64
	ds_read_b128 v[152:155], v100 offset:128
	ds_read_b128 v[168:171], v100 offset:192
	ds_read_b128 v[172:175], v100 offset:256
	ds_read_b128 v[176:179], v100 offset:320
	ds_read_b128 v[180:183], v100 offset:384
	ds_read_b128 v[184:187], v100 offset:448
	s_waitcnt vmcnt(11)
	v_lshlrev_b32_e32 v57, 16, v135
	v_mov_b32_e32 v97, v1
	v_or_b32_e32 v0, 1, v96
	v_or_b32_e32 v58, 2, v96
	v_mov_b32_e32 v59, v1
	v_or_b32_e32 v56, 3, v96
	s_add_i32 s11, s11, 1
	s_add_i32 s10, s10, 16
	s_cmp_eq_u32 s11, 8
	v_lshl_add_u64 v[60:61], v[96:97], 0, s[0:1]
	v_lshlrev_b64 v[60:61], 10, v[60:61]
	v_lshl_add_u64 v[60:61], v[92:93], 0, v[60:61]
	s_waitcnt lgkmcnt(6)
	v_mfma_f32_16x16x4_f32 v[52:55], v144, v4, 0
	v_mfma_f32_16x16x4_f32 v[188:191], v148, v8, 0
	v_mfma_f32_16x16x4_f32 v[52:55], v145, v5, v[52:55]
	v_mfma_f32_16x16x4_f32 v[188:191], v149, v9, v[188:191]
	v_mfma_f32_16x16x4_f32 v[52:55], v146, v6, v[52:55]
	v_mfma_f32_16x16x4_f32 v[188:191], v150, v10, v[188:191]
	v_mfma_f32_16x16x4_f32 v[52:55], v147, v7, v[52:55]
	v_mfma_f32_16x16x4_f32 v[188:191], v151, v11, v[188:191]
	s_waitcnt lgkmcnt(4)
	v_mfma_f32_16x16x4_f32 v[52:55], v152, v12, v[52:55]
	v_mfma_f32_16x16x4_f32 v[188:191], v168, v16, v[188:191]
	v_mfma_f32_16x16x4_f32 v[52:55], v153, v13, v[52:55]
	v_mfma_f32_16x16x4_f32 v[188:191], v169, v17, v[188:191]
	v_mfma_f32_16x16x4_f32 v[52:55], v154, v14, v[52:55]
	v_mfma_f32_16x16x4_f32 v[188:191], v170, v18, v[188:191]
	v_mfma_f32_16x16x4_f32 v[52:55], v155, v15, v[52:55]
	v_mfma_f32_16x16x4_f32 v[188:191], v171, v19, v[188:191]
	s_waitcnt lgkmcnt(2)
	v_mfma_f32_16x16x4_f32 v[52:55], v172, v89, v[52:55]
	v_mfma_f32_16x16x4_f32 v[188:191], v176, v120, v[188:191]
	v_mfma_f32_16x16x4_f32 v[52:55], v173, v117, v[52:55]
	v_mfma_f32_16x16x4_f32 v[188:191], v177, v121, v[188:191]
	v_mfma_f32_16x16x4_f32 v[52:55], v174, v118, v[52:55]
	v_mfma_f32_16x16x4_f32 v[188:191], v178, v122, v[188:191]
	v_mfma_f32_16x16x4_f32 v[52:55], v175, v119, v[52:55]
	v_mfma_f32_16x16x4_f32 v[188:191], v179, v123, v[188:191]
	s_waitcnt lgkmcnt(0)
	v_mfma_f32_16x16x4_f32 v[52:55], v180, v124, v[52:55]
	v_mfma_f32_16x16x4_f32 v[188:191], v184, v128, v[188:191]
	v_mfma_f32_16x16x4_f32 v[52:55], v181, v125, v[52:55]
	v_mfma_f32_16x16x4_f32 v[188:191], v185, v129, v[188:191]
	v_mfma_f32_16x16x4_f32 v[52:55], v182, v126, v[52:55]
	v_mfma_f32_16x16x4_f32 v[188:191], v186, v130, v[188:191]
	v_mfma_f32_16x16x4_f32 v[52:55], v183, v127, v[52:55]
	v_mfma_f32_16x16x4_f32 v[188:191], v187, v131, v[188:191]
	s_nop 9
	s_nop 1
	v_add_f32_e32 v52, v52, v188
	v_add_f32_e32 v53, v53, v189
	v_add_f32_e32 v54, v54, v190
	v_add_f32_e32 v55, v55, v191
	v_fma_f32 v52, v87, v57, v52
	v_mul_f32_e32 v57, v52, v52
	v_fmamk_f32 v57, v57, 0xbdd2d3e8, v196
	v_mul_f32_e32 v57, v52, v57
	v_exp_f32_e32 v57, v57
	s_nop 0
	v_add_f32_e32 v57, 1.0, v57
	v_rcp_f32_e32 v57, v57
	s_nop 0
	v_mul_f32_e32 v52, v52, v57
	v_bfe_u32 v57, v52, 16, 1
	v_add3_u32 v52, v52, v57, s80
	global_store_short_d16_hi v[60:61], v52, off
	v_lshl_add_u64 v[60:61], v[0:1], 0, s[0:1]
	s_waitcnt vmcnt(11)
	v_lshlrev_b32_e32 v0, 16, v134
	v_fma_f32 v0, v87, v0, v53
	v_mul_f32_e32 v52, v0, v0
	v_fmamk_f32 v52, v52, 0xbdd2d3e8, v196
	v_mul_f32_e32 v52, v0, v52
	v_exp_f32_e32 v52, v52
	v_mov_b32_e32 v57, v1
	v_add_f32_e32 v52, 1.0, v52
	v_rcp_f32_e32 v52, v52
	s_nop 0
	v_mul_f32_e32 v0, v0, v52
	v_bfe_u32 v52, v0, 16, 1
	v_add3_u32 v0, v0, v52, s80
	v_lshlrev_b64 v[52:53], 10, v[60:61]
	v_lshl_add_u64 v[52:53], v[92:93], 0, v[52:53]
	global_store_short_d16_hi v[52:53], v0, off
	s_waitcnt vmcnt(11)
	v_lshlrev_b32_e32 v0, 16, v133
	v_fma_f32 v0, v87, v0, v54
	v_mul_f32_e32 v54, v0, v0
	v_fmamk_f32 v54, v54, 0xbdd2d3e8, v196
	v_mul_f32_e32 v54, v0, v54
	v_exp_f32_e32 v54, v54
	v_lshl_add_u64 v[52:53], v[58:59], 0, s[0:1]
	v_lshlrev_b64 v[52:53], 10, v[52:53]
	v_lshl_add_u64 v[52:53], v[92:93], 0, v[52:53]
	v_add_f32_e32 v54, 1.0, v54
	v_rcp_f32_e32 v54, v54
	s_nop 0
	v_mul_f32_e32 v0, v0, v54
	v_bfe_u32 v54, v0, 16, 1
	v_add3_u32 v0, v0, v54, s80
	global_store_short_d16_hi v[52:53], v0, off
	s_waitcnt vmcnt(11)
	v_lshlrev_b32_e32 v0, 16, v132
	v_fmac_f32_e32 v55, v87, v0
	v_mul_f32_e32 v0, v55, v55
	v_fmamk_f32 v0, v0, 0xbdd2d3e8, v196
	v_mul_f32_e32 v0, v55, v0
	v_exp_f32_e32 v0, v0
	v_lshl_add_u64 v[52:53], v[56:57], 0, s[0:1]
	v_lshlrev_b64 v[52:53], 10, v[52:53]
	v_lshl_add_u64 v[52:53], v[92:93], 0, v[52:53]
	v_add_f32_e32 v0, 1.0, v0
	v_rcp_f32_e32 v0, v0
	s_nop 0
	v_mul_f32_e32 v0, v55, v0
	v_bfe_u32 v54, v0, 16, 1
	v_add3_u32 v0, v0, v54, s80
	global_store_short_d16_hi v[52:53], v0, off
	s_cbranch_scc0 .LBB0_149
	s_add_i32 s9, s9, s33
	s_cmpk_gt_i32 s9, 0xfff
	s_cbranch_scc0 .LBB0_141
